# P0 de-serialised: modulation GEMV k-loop with 16 row loads in flight, x/ctx copy 8/4 iterations in flight, silu table loads hoisted, no-item workgroups skip the table; barrier invalidate reorder
# speedup vs baseline: 1.0104x; 1.0104x over previous
; #define GAS __attribute__((address_space(1)))
; __device__ __forceinline__ unsigned cvtpk(float lo, float hi) { f32x2_t v = {lo, hi}; bf16x2_t b = __builtin_convertvector(v, bf16x2_t); return __builtin_bit_cast(unsigned, b); }
; __global__ void __launch_bounds__(512, 2) fwd_mega(Args args) {
;     ...
;                 const GAS f32x4* xs = (const GAS f32x4*)ap->in[0]; const GAS f32x4* cs = (const GAS f32x4*)ap->in[2]; GAS u32x4* xd = (GAS u32x4*)(ws + WS_X);
;                 const int nl = MLAT * DM / 8, nc = MCTX * DM / 8;
;                 const int cb0 = G > 144 ? 144 : 0, cnb = G - cb0;
;                 if (bx >= cb0) {
;                     for (int i = (bx - cb0) * 512 + tid; i < nl; i += cnb * 512) { const f32x4 a = xs[2 * i], c = xs[2 * i + 1]; xd[i] = (u32x4){cvtpk(a.x, a.y), cvtpk(a.z, a.w), cvtpk(c.x, c.y), cvtpk(c.z, c.w)}; }
.LBB0_1144:
	s_cmpk_gt_i32 s82, 0x90
	s_cselect_b32 s4, 0x90, 0
	s_cmp_ge_i32 s83, s4
	s_cbranch_scc0 .LBB0_1152
	s_waitcnt vmcnt(0) lgkmcnt(0)
	v_mov_b64_e32 v[2:3], s[0:1]
	flat_load_dwordx2 v[2:3], v[2:3] offset:16
	s_add_u32 s14, s34, 0xa780000
	s_addc_u32 s15, s35, 0
	s_sub_i32 s6, s83, s4
	v_lshl_add_u32 v4, s6, 9, v196
	s_mov_b32 s6, 0x200000
	s_sub_i32 s5, s82, s4
	v_cmp_gt_i32_e32 vcc, s6, v4
	v_ashrrev_i32_e32 v5, 31, v4
	v_lshlrev_b32_e32 v6, 1, v4
	s_and_saveexec_b64 s[20:21], vcc
	s_cbranch_execz .LBB0_1148
	v_mov_b64_e32 v[8:9], s[0:1]
	flat_load_dwordx2 v[8:9], v[8:9]
	s_lshl_b32 s22, s5, 9
	s_ashr_i32 s23, s22, 31
	s_lshl_b32 s6, s82, 10
	s_lshl_b32 s7, s4, 10
	v_lshl_add_u64 v[10:11], v[4:5], 4, s[14:15]
	s_lshl_b64 s[26:27], s[22:23], 4
	v_lshlrev_b32_e32 v12, 1, v4
	s_sub_i32 s6, s6, s7
	s_mov_b64 s[36:37], 0
	v_mov_b32_e32 v0, v4
	s_waitcnt vmcnt(0) lgkmcnt(0)
	v_readfirstlane_b32 s7, v0
	s_mul_i32 s40, s22, 7
	s_add_i32 s40, s40, 63
	s_mul_i32 s41, s22, 8
.Lxc_x_loop:
	s_add_i32 s43, s7, s40
	s_cmp_lt_i32 s43, 0x200000
	s_cbranch_scc0 .Lxc_x_done
	v_mov_b32_e32 v22, v12
	v_ashrrev_i32_e32 v23, 31, v22
	v_lshl_add_u64 v[24:25], v[22:23], 4, v[8:9]
	global_load_dwordx4 v[40:43], v[24:25], off
	global_load_dwordx4 v[44:47], v[24:25], off offset:16
	v_add_u32_e32 v22, s6, v22
	v_ashrrev_i32_e32 v23, 31, v22
	v_lshl_add_u64 v[26:27], v[22:23], 4, v[8:9]
	global_load_dwordx4 v[48:51], v[26:27], off
	global_load_dwordx4 v[52:55], v[26:27], off offset:16
	v_add_u32_e32 v22, s6, v22
	v_ashrrev_i32_e32 v23, 31, v22
	v_lshl_add_u64 v[28:29], v[22:23], 4, v[8:9]
	global_load_dwordx4 v[56:59], v[28:29], off
	global_load_dwordx4 v[60:63], v[28:29], off offset:16
	v_add_u32_e32 v22, s6, v22
	v_ashrrev_i32_e32 v23, 31, v22
	v_lshl_add_u64 v[30:31], v[22:23], 4, v[8:9]
	global_load_dwordx4 v[64:67], v[30:31], off
	global_load_dwordx4 v[68:71], v[30:31], off offset:16
	v_add_u32_e32 v22, s6, v22
	v_ashrrev_i32_e32 v23, 31, v22
	v_lshl_add_u64 v[32:33], v[22:23], 4, v[8:9]
	global_load_dwordx4 v[72:75], v[32:33], off
	global_load_dwordx4 v[76:79], v[32:33], off offset:16
	v_add_u32_e32 v22, s6, v22
	v_ashrrev_i32_e32 v23, 31, v22
	v_lshl_add_u64 v[34:35], v[22:23], 4, v[8:9]
	global_load_dwordx4 v[80:83], v[34:35], off
	global_load_dwordx4 v[84:87], v[34:35], off offset:16
	v_add_u32_e32 v22, s6, v22
	v_ashrrev_i32_e32 v23, 31, v22
	v_lshl_add_u64 v[36:37], v[22:23], 4, v[8:9]
	global_load_dwordx4 v[88:91], v[36:37], off
	global_load_dwordx4 v[92:95], v[36:37], off offset:16
	v_add_u32_e32 v22, s6, v22
	v_ashrrev_i32_e32 v23, 31, v22
	v_lshl_add_u64 v[38:39], v[22:23], 4, v[8:9]
	global_load_dwordx4 v[96:99], v[38:39], off
	global_load_dwordx4 v[100:103], v[38:39], off offset:16
	v_add_u32_e32 v22, s6, v22
	v_mov_b32_e32 v12, v22
	v_add_u32_e32 v0, s41, v0
	s_add_i32 s7, s7, s41
	s_waitcnt vmcnt(14)
	v_cvt_pk_bf16_f32 v40, v40, v41
	v_cvt_pk_bf16_f32 v41, v42, v43
	v_cvt_pk_bf16_f32 v42, v44, v45
	v_cvt_pk_bf16_f32 v43, v46, v47
	global_store_dwordx4 v[10:11], v[40:43], off
	v_lshl_add_u64 v[10:11], v[10:11], 0, s[26:27]
	s_waitcnt vmcnt(13)
	v_cvt_pk_bf16_f32 v48, v48, v49
	v_cvt_pk_bf16_f32 v49, v50, v51
	v_cvt_pk_bf16_f32 v50, v52, v53
	v_cvt_pk_bf16_f32 v51, v54, v55
	global_store_dwordx4 v[10:11], v[48:51], off
	v_lshl_add_u64 v[10:11], v[10:11], 0, s[26:27]
	s_waitcnt vmcnt(12)
	v_cvt_pk_bf16_f32 v56, v56, v57
	v_cvt_pk_bf16_f32 v57, v58, v59
	v_cvt_pk_bf16_f32 v58, v60, v61
	v_cvt_pk_bf16_f32 v59, v62, v63
	global_store_dwordx4 v[10:11], v[56:59], off
	v_lshl_add_u64 v[10:11], v[10:11], 0, s[26:27]
	s_waitcnt vmcnt(11)
	v_cvt_pk_bf16_f32 v64, v64, v65
	v_cvt_pk_bf16_f32 v65, v66, v67
	v_cvt_pk_bf16_f32 v66, v68, v69
	v_cvt_pk_bf16_f32 v67, v70, v71
	global_store_dwordx4 v[10:11], v[64:67], off
	v_lshl_add_u64 v[10:11], v[10:11], 0, s[26:27]
	s_waitcnt vmcnt(10)
	v_cvt_pk_bf16_f32 v72, v72, v73
	v_cvt_pk_bf16_f32 v73, v74, v75
	v_cvt_pk_bf16_f32 v74, v76, v77
	v_cvt_pk_bf16_f32 v75, v78, v79
	global_store_dwordx4 v[10:11], v[72:75], off
	v_lshl_add_u64 v[10:11], v[10:11], 0, s[26:27]
	s_waitcnt vmcnt(9)
	v_cvt_pk_bf16_f32 v80, v80, v81
	v_cvt_pk_bf16_f32 v81, v82, v83
	v_cvt_pk_bf16_f32 v82, v84, v85
	v_cvt_pk_bf16_f32 v83, v86, v87
	global_store_dwordx4 v[10:11], v[80:83], off
	v_lshl_add_u64 v[10:11], v[10:11], 0, s[26:27]
	s_waitcnt vmcnt(8)
	v_cvt_pk_bf16_f32 v88, v88, v89
	v_cvt_pk_bf16_f32 v89, v90, v91
	v_cvt_pk_bf16_f32 v90, v92, v93
	v_cvt_pk_bf16_f32 v91, v94, v95
	global_store_dwordx4 v[10:11], v[88:91], off
	v_lshl_add_u64 v[10:11], v[10:11], 0, s[26:27]
	s_waitcnt vmcnt(7)
	v_cvt_pk_bf16_f32 v96, v96, v97
	v_cvt_pk_bf16_f32 v97, v98, v99
	v_cvt_pk_bf16_f32 v98, v100, v101
	v_cvt_pk_bf16_f32 v99, v102, v103
	global_store_dwordx4 v[10:11], v[96:99], off
	v_lshl_add_u64 v[10:11], v[10:11], 0, s[26:27]
	s_branch .Lxc_x_loop
.Lxc_x_done:
	s_mov_b32 s43, 0x200000
	v_cmp_gt_i32_e32 vcc, s43, v0
	s_and_b64 exec, exec, vcc
	s_cbranch_execz .LBB0_1148

; __device__ __forceinline__ unsigned cvtpk(float lo, float hi) { f32x2_t v = {lo, hi}; bf16x2_t b = __builtin_convertvector(v, bf16x2_t); return __builtin_bit_cast(unsigned, b); }
; __global__ void __launch_bounds__(512, 2) fwd_mega(Args args) {
;     ...
;                     for (int i = (bx - cb0) * 512 + tid; i < nc; i += cnb * 512) { const f32x4 a = cs[2 * i], c = cs[2 * i + 1]; xd[nl + i] = (u32x4){cvtpk(a.x, a.y), cvtpk(a.z, a.w), cvtpk(c.x, c.y), cvtpk(c.z, c.w)}; }
.LBB0_1148:
	s_or_b64 exec, exec, s[20:21]
	s_mov_b32 s6, 0x40000
	v_cmp_gt_i32_e32 vcc, s6, v4
	s_and_saveexec_b64 s[20:21], vcc
	s_cbranch_execz .LBB0_1151
	s_lshl_b32 s22, s5, 9
	s_lshl_b32 s5, s82, 10
	s_lshl_b32 s4, s4, 10
	v_lshl_add_u64 v[8:9], v[4:5], 4, s[14:15]
	s_mov_b64 s[6:7], 0x2000000
	s_ashr_i32 s23, s22, 31
	s_sub_i32 s4, s5, s4
	v_lshl_add_u64 v[8:9], v[8:9], 0, s[6:7]
	s_lshl_b64 s[14:15], s[22:23], 4
	s_mov_b64 s[26:27], 0
	s_waitcnt vmcnt(0) lgkmcnt(0)
	v_readfirstlane_b32 s7, v4
	s_mul_i32 s40, s22, 3
	s_add_i32 s40, s40, 63
	s_mul_i32 s41, s22, 4
.Lxc_c_loop:
	s_add_i32 s43, s7, s40
	s_cmp_lt_i32 s43, 0x40000
	s_cbranch_scc0 .Lxc_c_done
	v_mov_b32_e32 v22, v6
	v_ashrrev_i32_e32 v23, 31, v22
	v_lshl_add_u64 v[24:25], v[22:23], 4, v[2:3]
	global_load_dwordx4 v[40:43], v[24:25], off
	global_load_dwordx4 v[44:47], v[24:25], off offset:16
	v_add_u32_e32 v22, s4, v22
	v_ashrrev_i32_e32 v23, 31, v22
	v_lshl_add_u64 v[26:27], v[22:23], 4, v[2:3]
	global_load_dwordx4 v[48:51], v[26:27], off
	global_load_dwordx4 v[52:55], v[26:27], off offset:16
	v_add_u32_e32 v22, s4, v22
	v_ashrrev_i32_e32 v23, 31, v22
	v_lshl_add_u64 v[28:29], v[22:23], 4, v[2:3]
	global_load_dwordx4 v[56:59], v[28:29], off
	global_load_dwordx4 v[60:63], v[28:29], off offset:16
	v_add_u32_e32 v22, s4, v22
	v_ashrrev_i32_e32 v23, 31, v22
	v_lshl_add_u64 v[30:31], v[22:23], 4, v[2:3]
	global_load_dwordx4 v[64:67], v[30:31], off
	global_load_dwordx4 v[68:71], v[30:31], off offset:16
	v_add_u32_e32 v22, s4, v22
	v_mov_b32_e32 v6, v22
	v_add_u32_e32 v4, s41, v4
	s_add_i32 s7, s7, s41
	s_waitcnt vmcnt(6)
	v_cvt_pk_bf16_f32 v40, v40, v41
	v_cvt_pk_bf16_f32 v41, v42, v43
	v_cvt_pk_bf16_f32 v42, v44, v45
	v_cvt_pk_bf16_f32 v43, v46, v47
	global_store_dwordx4 v[8:9], v[40:43], off
	v_lshl_add_u64 v[8:9], v[8:9], 0, s[14:15]
	s_waitcnt vmcnt(5)
	v_cvt_pk_bf16_f32 v48, v48, v49
	v_cvt_pk_bf16_f32 v49, v50, v51
	v_cvt_pk_bf16_f32 v50, v52, v53
	v_cvt_pk_bf16_f32 v51, v54, v55
	global_store_dwordx4 v[8:9], v[48:51], off
	v_lshl_add_u64 v[8:9], v[8:9], 0, s[14:15]
	s_waitcnt vmcnt(4)
	v_cvt_pk_bf16_f32 v56, v56, v57
	v_cvt_pk_bf16_f32 v57, v58, v59
	v_cvt_pk_bf16_f32 v58, v60, v61
	v_cvt_pk_bf16_f32 v59, v62, v63
	global_store_dwordx4 v[8:9], v[56:59], off
	v_lshl_add_u64 v[8:9], v[8:9], 0, s[14:15]
	s_waitcnt vmcnt(3)
	v_cvt_pk_bf16_f32 v64, v64, v65
	v_cvt_pk_bf16_f32 v65, v66, v67
	v_cvt_pk_bf16_f32 v66, v68, v69
	v_cvt_pk_bf16_f32 v67, v70, v71
	global_store_dwordx4 v[8:9], v[64:67], off
	v_lshl_add_u64 v[8:9], v[8:9], 0, s[14:15]
	s_branch .Lxc_c_loop
.Lxc_c_done:
	s_mov_b32 s43, 0x40000
	v_cmp_gt_i32_e32 vcc, s43, v4
	s_and_b64 exec, exec, vcc
	s_cbranch_execz .LBB0_1151

; #define LAS __attribute__((address_space(3)))
; __global__ void __launch_bounds__(512, 2) fwd_mega(Args args) {
;     ...
;             __syncthreads();
;             {
;                 LAS float* S = (LAS float*)ldsl;
;                 LAS float* red = (LAS float*)(ldsl + 36864);
;                 for (int i = tid; i < 9 * DM; i += 512) { const int r = i >> 10, k = i & 1023; const float v = r < 8 ? ap->in[1][r * DM + k] : ap->in[3][k]; S[i] = v / (1.0f + expf(-v)); }
;                 __syncthreads();
;                 for (int item = bx; item < DEPTH * 36; item += G) {
.LBB0_1157:
	s_or_b64 exec, exec, s[14:15]
	s_cmpk_gt_i32 s83, 0x8f
	s_cbranch_scc1 .LBB0_1172
	s_movk_i32 s4, 0x2400
	v_cmp_gt_i32_e32 vcc, s4, v196
	s_waitcnt vmcnt(0) lgkmcnt(0)
	s_barrier
	s_and_saveexec_b64 s[14:15], vcc
	s_cbranch_execz .LBB0_1164
	v_ashrrev_i32_e32 v197, 31, v196
	v_readlane_b32 s4, v255, 17
	v_lshlrev_b64 v[2:3], 2, v[196:197]
	s_load_dwordx2 s[20:21], s[0:1], 0x8
	s_load_dwordx2 s[22:23], s[0:1], 0x18
	v_lshl_add_u32 v6, v198, 2, s4
	s_mov_b64 s[26:27], 0x800
	s_mov_b32 s42, 0xbfb8aa3b
	s_mov_b32 s43, 0x42ce8ed0
	s_mov_b32 s8, 0xc2b17218
	s_waitcnt lgkmcnt(0)
	v_lshl_add_u64 v[8:9], v[2:3], 0, s[20:21]
	v_lshl_add_u64 v[10:11], v[2:3], 0, s[22:23]
	global_load_dword v20, v[8:9], off
	v_lshl_add_u64 v[8:9], v[8:9], 0, s[26:27]
	global_load_dword v21, v[8:9], off
	v_lshl_add_u64 v[8:9], v[8:9], 0, s[26:27]
	global_load_dword v22, v[8:9], off
	v_lshl_add_u64 v[8:9], v[8:9], 0, s[26:27]
	global_load_dword v23, v[8:9], off
	v_lshl_add_u64 v[8:9], v[8:9], 0, s[26:27]
	global_load_dword v24, v[8:9], off
	v_lshl_add_u64 v[8:9], v[8:9], 0, s[26:27]
	global_load_dword v25, v[8:9], off
	v_lshl_add_u64 v[8:9], v[8:9], 0, s[26:27]
	global_load_dword v26, v[8:9], off
	v_lshl_add_u64 v[8:9], v[8:9], 0, s[26:27]
	global_load_dword v27, v[8:9], off
	v_lshl_add_u64 v[8:9], v[8:9], 0, s[26:27]
	global_load_dword v28, v[8:9], off
	v_lshl_add_u64 v[8:9], v[8:9], 0, s[26:27]
	global_load_dword v29, v[8:9], off
	v_lshl_add_u64 v[8:9], v[8:9], 0, s[26:27]
	global_load_dword v30, v[8:9], off
	v_lshl_add_u64 v[8:9], v[8:9], 0, s[26:27]
	global_load_dword v31, v[8:9], off
	v_lshl_add_u64 v[8:9], v[8:9], 0, s[26:27]
	global_load_dword v32, v[8:9], off
	v_lshl_add_u64 v[8:9], v[8:9], 0, s[26:27]
	global_load_dword v33, v[8:9], off
	v_lshl_add_u64 v[8:9], v[8:9], 0, s[26:27]
	global_load_dword v34, v[8:9], off
	v_lshl_add_u64 v[8:9], v[8:9], 0, s[26:27]
	global_load_dword v35, v[8:9], off
	global_load_dword v36, v[10:11], off
	global_load_dword v37, v[10:11], off offset:2048
	s_waitcnt vmcnt(17)
	v_mul_f32_e32 v4, 0xbfb8aa3b, v20
	v_rndne_f32_e32 v5, v4
	v_fma_f32 v8, v20, s42, -v4
	v_sub_f32_e32 v4, v4, v5
	v_fmac_f32_e32 v8, 0xb2a5705f, v20
	v_add_f32_e32 v4, v4, v8
	v_exp_f32_e32 v4, v4
	v_cvt_i32_f32_e32 v5, v5
	v_cmp_nlt_f32_e64 s[40:41], s43, v20
	v_ldexp_f32 v4, v4, v5
	s_nop 1
	v_cndmask_b32_e64 v4, 0, v4, s[40:41]
	v_cmp_ngt_f32_e64 s[40:41], s8, v20
	s_nop 1
	v_cndmask_b32_e64 v4, v228, v4, s[40:41]
	v_add_f32_e32 v4, 1.0, v4
	v_div_scale_f32 v5, s[4:5], v4, v4, v20
	v_rcp_f32_e32 v7, v5
	v_div_scale_f32 v9, vcc, v20, v4, v20
	v_fma_f32 v10, -v5, v7, 1.0
	v_fmac_f32_e32 v7, v10, v7
	v_mul_f32_e32 v10, v9, v7
	v_fma_f32 v11, -v5, v10, v9
	v_fmac_f32_e32 v10, v11, v7
	v_fma_f32 v5, -v5, v10, v9
	v_div_fmas_f32 v5, v5, v7, v10
	v_div_fixup_f32 v12, v5, v4, v20
	ds_write_b32 v6, v12
	s_waitcnt vmcnt(16)
	v_mul_f32_e32 v4, 0xbfb8aa3b, v21
	v_rndne_f32_e32 v5, v4
	v_fma_f32 v8, v21, s42, -v4
	v_sub_f32_e32 v4, v4, v5
	v_fmac_f32_e32 v8, 0xb2a5705f, v21
	v_add_f32_e32 v4, v4, v8
	v_exp_f32_e32 v4, v4
	v_cvt_i32_f32_e32 v5, v5
	v_cmp_nlt_f32_e64 s[40:41], s43, v21
	v_ldexp_f32 v4, v4, v5
	s_nop 1
	v_cndmask_b32_e64 v4, 0, v4, s[40:41]
	v_cmp_ngt_f32_e64 s[40:41], s8, v21
	s_nop 1
	v_cndmask_b32_e64 v4, v228, v4, s[40:41]
	v_add_f32_e32 v4, 1.0, v4
	v_div_scale_f32 v5, s[4:5], v4, v4, v21
	v_rcp_f32_e32 v7, v5
	v_div_scale_f32 v9, vcc, v21, v4, v21
	v_fma_f32 v10, -v5, v7, 1.0
	v_fmac_f32_e32 v7, v10, v7
	v_mul_f32_e32 v10, v9, v7
	v_fma_f32 v11, -v5, v10, v9
	v_fmac_f32_e32 v10, v11, v7
	v_fma_f32 v5, -v5, v10, v9
	v_div_fmas_f32 v5, v5, v7, v10
	v_div_fixup_f32 v12, v5, v4, v21
	ds_write_b32 v6, v12 offset:2048
	s_waitcnt vmcnt(15)
	v_mul_f32_e32 v4, 0xbfb8aa3b, v22
	v_rndne_f32_e32 v5, v4
	v_fma_f32 v8, v22, s42, -v4
	v_sub_f32_e32 v4, v4, v5
	v_fmac_f32_e32 v8, 0xb2a5705f, v22
	v_add_f32_e32 v4, v4, v8
	v_exp_f32_e32 v4, v4
	v_cvt_i32_f32_e32 v5, v5
	v_cmp_nlt_f32_e64 s[40:41], s43, v22
	v_ldexp_f32 v4, v4, v5
	s_nop 1
	v_cndmask_b32_e64 v4, 0, v4, s[40:41]
	v_cmp_ngt_f32_e64 s[40:41], s8, v22
	s_nop 1
	v_cndmask_b32_e64 v4, v228, v4, s[40:41]
	v_add_f32_e32 v4, 1.0, v4
	v_div_scale_f32 v5, s[4:5], v4, v4, v22
	v_rcp_f32_e32 v7, v5
	v_div_scale_f32 v9, vcc, v22, v4, v22
	v_fma_f32 v10, -v5, v7, 1.0
	v_fmac_f32_e32 v7, v10, v7
	v_mul_f32_e32 v10, v9, v7
	v_fma_f32 v11, -v5, v10, v9
	v_fmac_f32_e32 v10, v11, v7
	v_fma_f32 v5, -v5, v10, v9
	v_div_fmas_f32 v5, v5, v7, v10
	v_div_fixup_f32 v12, v5, v4, v22
	ds_write_b32 v6, v12 offset:4096
	s_waitcnt vmcnt(14)
	v_mul_f32_e32 v4, 0xbfb8aa3b, v23
	v_rndne_f32_e32 v5, v4
	v_fma_f32 v8, v23, s42, -v4
	v_sub_f32_e32 v4, v4, v5
	v_fmac_f32_e32 v8, 0xb2a5705f, v23
	v_add_f32_e32 v4, v4, v8
	v_exp_f32_e32 v4, v4
	v_cvt_i32_f32_e32 v5, v5
	v_cmp_nlt_f32_e64 s[40:41], s43, v23
	v_ldexp_f32 v4, v4, v5
	s_nop 1
	v_cndmask_b32_e64 v4, 0, v4, s[40:41]
	v_cmp_ngt_f32_e64 s[40:41], s8, v23
	s_nop 1
	v_cndmask_b32_e64 v4, v228, v4, s[40:41]
	v_add_f32_e32 v4, 1.0, v4
	v_div_scale_f32 v5, s[4:5], v4, v4, v23
	v_rcp_f32_e32 v7, v5
	v_div_scale_f32 v9, vcc, v23, v4, v23
	v_fma_f32 v10, -v5, v7, 1.0
	v_fmac_f32_e32 v7, v10, v7
	v_mul_f32_e32 v10, v9, v7
	v_fma_f32 v11, -v5, v10, v9
	v_fmac_f32_e32 v10, v11, v7
	v_fma_f32 v5, -v5, v10, v9
	v_div_fmas_f32 v5, v5, v7, v10
	v_div_fixup_f32 v12, v5, v4, v23
	ds_write_b32 v6, v12 offset:6144
	s_waitcnt vmcnt(13)
; __global__ void __launch_bounds__(512, 2) fwd_mega(Args args) {
;     ...
;                 for (int i = tid; i < 9 * DM; i += 512) { const int r = i >> 10, k = i & 1023; const float v = r < 8 ? ap->in[1][r * DM + k] : ap->in[3][k]; S[i] = v / (1.0f + expf(-v)); }
	v_mul_f32_e32 v4, 0xbfb8aa3b, v24
	v_rndne_f32_e32 v5, v4
	v_fma_f32 v8, v24, s42, -v4
	v_sub_f32_e32 v4, v4, v5
	v_fmac_f32_e32 v8, 0xb2a5705f, v24
	v_add_f32_e32 v4, v4, v8
	v_exp_f32_e32 v4, v4
	v_cvt_i32_f32_e32 v5, v5
	v_cmp_nlt_f32_e64 s[40:41], s43, v24
	v_ldexp_f32 v4, v4, v5
	s_nop 1
	v_cndmask_b32_e64 v4, 0, v4, s[40:41]
	v_cmp_ngt_f32_e64 s[40:41], s8, v24
	s_nop 1
	v_cndmask_b32_e64 v4, v228, v4, s[40:41]
	v_add_f32_e32 v4, 1.0, v4
	v_div_scale_f32 v5, s[4:5], v4, v4, v24
	v_rcp_f32_e32 v7, v5
	v_div_scale_f32 v9, vcc, v24, v4, v24
	v_fma_f32 v10, -v5, v7, 1.0
	v_fmac_f32_e32 v7, v10, v7
	v_mul_f32_e32 v10, v9, v7
	v_fma_f32 v11, -v5, v10, v9
	v_fmac_f32_e32 v10, v11, v7
	v_fma_f32 v5, -v5, v10, v9
	v_div_fmas_f32 v5, v5, v7, v10
	v_div_fixup_f32 v12, v5, v4, v24
	ds_write_b32 v6, v12 offset:8192
	s_waitcnt vmcnt(12)
	v_mul_f32_e32 v4, 0xbfb8aa3b, v25
	v_rndne_f32_e32 v5, v4
	v_fma_f32 v8, v25, s42, -v4
	v_sub_f32_e32 v4, v4, v5
	v_fmac_f32_e32 v8, 0xb2a5705f, v25
	v_add_f32_e32 v4, v4, v8
	v_exp_f32_e32 v4, v4
	v_cvt_i32_f32_e32 v5, v5
	v_cmp_nlt_f32_e64 s[40:41], s43, v25
	v_ldexp_f32 v4, v4, v5
	s_nop 1
	v_cndmask_b32_e64 v4, 0, v4, s[40:41]
	v_cmp_ngt_f32_e64 s[40:41], s8, v25
	s_nop 1
	v_cndmask_b32_e64 v4, v228, v4, s[40:41]
	v_add_f32_e32 v4, 1.0, v4
	v_div_scale_f32 v5, s[4:5], v4, v4, v25
	v_rcp_f32_e32 v7, v5
	v_div_scale_f32 v9, vcc, v25, v4, v25
	v_fma_f32 v10, -v5, v7, 1.0
	v_fmac_f32_e32 v7, v10, v7
	v_mul_f32_e32 v10, v9, v7
	v_fma_f32 v11, -v5, v10, v9
	v_fmac_f32_e32 v10, v11, v7
	v_fma_f32 v5, -v5, v10, v9
	v_div_fmas_f32 v5, v5, v7, v10
	v_div_fixup_f32 v12, v5, v4, v25
	ds_write_b32 v6, v12 offset:10240
	s_waitcnt vmcnt(11)
	v_mul_f32_e32 v4, 0xbfb8aa3b, v26
	v_rndne_f32_e32 v5, v4
	v_fma_f32 v8, v26, s42, -v4
	v_sub_f32_e32 v4, v4, v5
	v_fmac_f32_e32 v8, 0xb2a5705f, v26
	v_add_f32_e32 v4, v4, v8
	v_exp_f32_e32 v4, v4
	v_cvt_i32_f32_e32 v5, v5
	v_cmp_nlt_f32_e64 s[40:41], s43, v26
	v_ldexp_f32 v4, v4, v5
	s_nop 1
	v_cndmask_b32_e64 v4, 0, v4, s[40:41]
	v_cmp_ngt_f32_e64 s[40:41], s8, v26
	s_nop 1
	v_cndmask_b32_e64 v4, v228, v4, s[40:41]
	v_add_f32_e32 v4, 1.0, v4
	v_div_scale_f32 v5, s[4:5], v4, v4, v26
	v_rcp_f32_e32 v7, v5
	v_div_scale_f32 v9, vcc, v26, v4, v26
	v_fma_f32 v10, -v5, v7, 1.0
	v_fmac_f32_e32 v7, v10, v7
	v_mul_f32_e32 v10, v9, v7
	v_fma_f32 v11, -v5, v10, v9
	v_fmac_f32_e32 v10, v11, v7
	v_fma_f32 v5, -v5, v10, v9
	v_div_fmas_f32 v5, v5, v7, v10
	v_div_fixup_f32 v12, v5, v4, v26
	ds_write_b32 v6, v12 offset:12288
	s_waitcnt vmcnt(10)
	v_mul_f32_e32 v4, 0xbfb8aa3b, v27
	v_rndne_f32_e32 v5, v4
	v_fma_f32 v8, v27, s42, -v4
	v_sub_f32_e32 v4, v4, v5
	v_fmac_f32_e32 v8, 0xb2a5705f, v27
	v_add_f32_e32 v4, v4, v8
	v_exp_f32_e32 v4, v4
	v_cvt_i32_f32_e32 v5, v5
	v_cmp_nlt_f32_e64 s[40:41], s43, v27
	v_ldexp_f32 v4, v4, v5
	s_nop 1
	v_cndmask_b32_e64 v4, 0, v4, s[40:41]
	v_cmp_ngt_f32_e64 s[40:41], s8, v27
	s_nop 1
	v_cndmask_b32_e64 v4, v228, v4, s[40:41]
	v_add_f32_e32 v4, 1.0, v4
	v_div_scale_f32 v5, s[4:5], v4, v4, v27
	v_rcp_f32_e32 v7, v5
	v_div_scale_f32 v9, vcc, v27, v4, v27
	v_fma_f32 v10, -v5, v7, 1.0
	v_fmac_f32_e32 v7, v10, v7
	v_mul_f32_e32 v10, v9, v7
	v_fma_f32 v11, -v5, v10, v9
	v_fmac_f32_e32 v10, v11, v7
	v_fma_f32 v5, -v5, v10, v9
	v_div_fmas_f32 v5, v5, v7, v10
	v_div_fixup_f32 v12, v5, v4, v27
	ds_write_b32 v6, v12 offset:14336
	s_waitcnt vmcnt(9)
	v_mul_f32_e32 v4, 0xbfb8aa3b, v28
	v_rndne_f32_e32 v5, v4
	v_fma_f32 v8, v28, s42, -v4
	v_sub_f32_e32 v4, v4, v5
	v_fmac_f32_e32 v8, 0xb2a5705f, v28
	v_add_f32_e32 v4, v4, v8
	v_exp_f32_e32 v4, v4
	v_cvt_i32_f32_e32 v5, v5
	v_cmp_nlt_f32_e64 s[40:41], s43, v28
	v_ldexp_f32 v4, v4, v5
	s_nop 1
	v_cndmask_b32_e64 v4, 0, v4, s[40:41]
	v_cmp_ngt_f32_e64 s[40:41], s8, v28
	s_nop 1
	v_cndmask_b32_e64 v4, v228, v4, s[40:41]
	v_add_f32_e32 v4, 1.0, v4
	v_div_scale_f32 v5, s[4:5], v4, v4, v28
	v_rcp_f32_e32 v7, v5
	v_div_scale_f32 v9, vcc, v28, v4, v28
	v_fma_f32 v10, -v5, v7, 1.0
	v_fmac_f32_e32 v7, v10, v7
	v_mul_f32_e32 v10, v9, v7
	v_fma_f32 v11, -v5, v10, v9
	v_fmac_f32_e32 v10, v11, v7
	v_fma_f32 v5, -v5, v10, v9
	v_div_fmas_f32 v5, v5, v7, v10
	v_div_fixup_f32 v12, v5, v4, v28
	ds_write_b32 v6, v12 offset:16384
	s_waitcnt vmcnt(8)
	v_mul_f32_e32 v4, 0xbfb8aa3b, v29
	v_rndne_f32_e32 v5, v4
	v_fma_f32 v8, v29, s42, -v4
	v_sub_f32_e32 v4, v4, v5
	v_fmac_f32_e32 v8, 0xb2a5705f, v29
	v_add_f32_e32 v4, v4, v8
	v_exp_f32_e32 v4, v4
	v_cvt_i32_f32_e32 v5, v5
	v_cmp_nlt_f32_e64 s[40:41], s43, v29
	v_ldexp_f32 v4, v4, v5
	s_nop 1
	v_cndmask_b32_e64 v4, 0, v4, s[40:41]
	v_cmp_ngt_f32_e64 s[40:41], s8, v29
	s_nop 1
	v_cndmask_b32_e64 v4, v228, v4, s[40:41]
	v_add_f32_e32 v4, 1.0, v4
	v_div_scale_f32 v5, s[4:5], v4, v4, v29
	v_rcp_f32_e32 v7, v5
	v_div_scale_f32 v9, vcc, v29, v4, v29
	v_fma_f32 v10, -v5, v7, 1.0
	v_fmac_f32_e32 v7, v10, v7
	v_mul_f32_e32 v10, v9, v7
	v_fma_f32 v11, -v5, v10, v9
	v_fmac_f32_e32 v10, v11, v7
	v_fma_f32 v5, -v5, v10, v9
	v_div_fmas_f32 v5, v5, v7, v10
	v_div_fixup_f32 v12, v5, v4, v29
	ds_write_b32 v6, v12 offset:18432
	s_waitcnt vmcnt(7)
	v_mul_f32_e32 v4, 0xbfb8aa3b, v30
	v_rndne_f32_e32 v5, v4
	v_fma_f32 v8, v30, s42, -v4
	v_sub_f32_e32 v4, v4, v5
	v_fmac_f32_e32 v8, 0xb2a5705f, v30
	v_add_f32_e32 v4, v4, v8
	v_exp_f32_e32 v4, v4
	v_cvt_i32_f32_e32 v5, v5
	v_cmp_nlt_f32_e64 s[40:41], s43, v30
	v_ldexp_f32 v4, v4, v5
	s_nop 1
	v_cndmask_b32_e64 v4, 0, v4, s[40:41]
	v_cmp_ngt_f32_e64 s[40:41], s8, v30
	s_nop 1
	v_cndmask_b32_e64 v4, v228, v4, s[40:41]
	v_add_f32_e32 v4, 1.0, v4
	v_div_scale_f32 v5, s[4:5], v4, v4, v30
	v_rcp_f32_e32 v7, v5
	v_div_scale_f32 v9, vcc, v30, v4, v30
	v_fma_f32 v10, -v5, v7, 1.0
	v_fmac_f32_e32 v7, v10, v7
	v_mul_f32_e32 v10, v9, v7
	v_fma_f32 v11, -v5, v10, v9
	v_fmac_f32_e32 v10, v11, v7
	v_fma_f32 v5, -v5, v10, v9
	v_div_fmas_f32 v5, v5, v7, v10
	v_div_fixup_f32 v12, v5, v4, v30
	ds_write_b32 v6, v12 offset:20480
	s_waitcnt vmcnt(6)
; __global__ void __launch_bounds__(512, 2) fwd_mega(Args args) {
;     ...
;                 for (int i = tid; i < 9 * DM; i += 512) { const int r = i >> 10, k = i & 1023; const float v = r < 8 ? ap->in[1][r * DM + k] : ap->in[3][k]; S[i] = v / (1.0f + expf(-v)); }
	v_mul_f32_e32 v4, 0xbfb8aa3b, v31
	v_rndne_f32_e32 v5, v4
	v_fma_f32 v8, v31, s42, -v4
	v_sub_f32_e32 v4, v4, v5
	v_fmac_f32_e32 v8, 0xb2a5705f, v31
	v_add_f32_e32 v4, v4, v8
	v_exp_f32_e32 v4, v4
	v_cvt_i32_f32_e32 v5, v5
	v_cmp_nlt_f32_e64 s[40:41], s43, v31
	v_ldexp_f32 v4, v4, v5
	s_nop 1
	v_cndmask_b32_e64 v4, 0, v4, s[40:41]
	v_cmp_ngt_f32_e64 s[40:41], s8, v31
	s_nop 1
	v_cndmask_b32_e64 v4, v228, v4, s[40:41]
	v_add_f32_e32 v4, 1.0, v4
	v_div_scale_f32 v5, s[4:5], v4, v4, v31
	v_rcp_f32_e32 v7, v5
	v_div_scale_f32 v9, vcc, v31, v4, v31
	v_fma_f32 v10, -v5, v7, 1.0
	v_fmac_f32_e32 v7, v10, v7
	v_mul_f32_e32 v10, v9, v7
	v_fma_f32 v11, -v5, v10, v9
	v_fmac_f32_e32 v10, v11, v7
	v_fma_f32 v5, -v5, v10, v9
	v_div_fmas_f32 v5, v5, v7, v10
	v_div_fixup_f32 v12, v5, v4, v31
	ds_write_b32 v6, v12 offset:22528
	s_waitcnt vmcnt(5)
	v_mul_f32_e32 v4, 0xbfb8aa3b, v32
	v_rndne_f32_e32 v5, v4
	v_fma_f32 v8, v32, s42, -v4
	v_sub_f32_e32 v4, v4, v5
	v_fmac_f32_e32 v8, 0xb2a5705f, v32
	v_add_f32_e32 v4, v4, v8
	v_exp_f32_e32 v4, v4
	v_cvt_i32_f32_e32 v5, v5
	v_cmp_nlt_f32_e64 s[40:41], s43, v32
	v_ldexp_f32 v4, v4, v5
	s_nop 1
	v_cndmask_b32_e64 v4, 0, v4, s[40:41]
	v_cmp_ngt_f32_e64 s[40:41], s8, v32
	s_nop 1
	v_cndmask_b32_e64 v4, v228, v4, s[40:41]
	v_add_f32_e32 v4, 1.0, v4
	v_div_scale_f32 v5, s[4:5], v4, v4, v32
	v_rcp_f32_e32 v7, v5
	v_div_scale_f32 v9, vcc, v32, v4, v32
	v_fma_f32 v10, -v5, v7, 1.0
	v_fmac_f32_e32 v7, v10, v7
	v_mul_f32_e32 v10, v9, v7
	v_fma_f32 v11, -v5, v10, v9
	v_fmac_f32_e32 v10, v11, v7
	v_fma_f32 v5, -v5, v10, v9
	v_div_fmas_f32 v5, v5, v7, v10
	v_div_fixup_f32 v12, v5, v4, v32
	ds_write_b32 v6, v12 offset:24576
	s_waitcnt vmcnt(4)
	v_mul_f32_e32 v4, 0xbfb8aa3b, v33
	v_rndne_f32_e32 v5, v4
	v_fma_f32 v8, v33, s42, -v4
	v_sub_f32_e32 v4, v4, v5
	v_fmac_f32_e32 v8, 0xb2a5705f, v33
	v_add_f32_e32 v4, v4, v8
	v_exp_f32_e32 v4, v4
	v_cvt_i32_f32_e32 v5, v5
	v_cmp_nlt_f32_e64 s[40:41], s43, v33
	v_ldexp_f32 v4, v4, v5
	s_nop 1
	v_cndmask_b32_e64 v4, 0, v4, s[40:41]
	v_cmp_ngt_f32_e64 s[40:41], s8, v33
	s_nop 1
	v_cndmask_b32_e64 v4, v228, v4, s[40:41]
	v_add_f32_e32 v4, 1.0, v4
	v_div_scale_f32 v5, s[4:5], v4, v4, v33
	v_rcp_f32_e32 v7, v5
	v_div_scale_f32 v9, vcc, v33, v4, v33
	v_fma_f32 v10, -v5, v7, 1.0
	v_fmac_f32_e32 v7, v10, v7
	v_mul_f32_e32 v10, v9, v7
	v_fma_f32 v11, -v5, v10, v9
	v_fmac_f32_e32 v10, v11, v7
	v_fma_f32 v5, -v5, v10, v9
	v_div_fmas_f32 v5, v5, v7, v10
	v_div_fixup_f32 v12, v5, v4, v33
	ds_write_b32 v6, v12 offset:26624
	s_waitcnt vmcnt(3)
	v_mul_f32_e32 v4, 0xbfb8aa3b, v34
	v_rndne_f32_e32 v5, v4
	v_fma_f32 v8, v34, s42, -v4
	v_sub_f32_e32 v4, v4, v5
	v_fmac_f32_e32 v8, 0xb2a5705f, v34
	v_add_f32_e32 v4, v4, v8
	v_exp_f32_e32 v4, v4
	v_cvt_i32_f32_e32 v5, v5
	v_cmp_nlt_f32_e64 s[40:41], s43, v34
	v_ldexp_f32 v4, v4, v5
	s_nop 1
	v_cndmask_b32_e64 v4, 0, v4, s[40:41]
	v_cmp_ngt_f32_e64 s[40:41], s8, v34
	s_nop 1
	v_cndmask_b32_e64 v4, v228, v4, s[40:41]
	v_add_f32_e32 v4, 1.0, v4
	v_div_scale_f32 v5, s[4:5], v4, v4, v34
	v_rcp_f32_e32 v7, v5
	v_div_scale_f32 v9, vcc, v34, v4, v34
	v_fma_f32 v10, -v5, v7, 1.0
	v_fmac_f32_e32 v7, v10, v7
	v_mul_f32_e32 v10, v9, v7
	v_fma_f32 v11, -v5, v10, v9
	v_fmac_f32_e32 v10, v11, v7
	v_fma_f32 v5, -v5, v10, v9
	v_div_fmas_f32 v5, v5, v7, v10
	v_div_fixup_f32 v12, v5, v4, v34
	ds_write_b32 v6, v12 offset:28672
	s_waitcnt vmcnt(2)
	v_mul_f32_e32 v4, 0xbfb8aa3b, v35
	v_rndne_f32_e32 v5, v4
	v_fma_f32 v8, v35, s42, -v4
	v_sub_f32_e32 v4, v4, v5
	v_fmac_f32_e32 v8, 0xb2a5705f, v35
	v_add_f32_e32 v4, v4, v8
	v_exp_f32_e32 v4, v4
	v_cvt_i32_f32_e32 v5, v5
	v_cmp_nlt_f32_e64 s[40:41], s43, v35
	v_ldexp_f32 v4, v4, v5
	s_nop 1
	v_cndmask_b32_e64 v4, 0, v4, s[40:41]
	v_cmp_ngt_f32_e64 s[40:41], s8, v35
	s_nop 1
	v_cndmask_b32_e64 v4, v228, v4, s[40:41]
	v_add_f32_e32 v4, 1.0, v4
	v_div_scale_f32 v5, s[4:5], v4, v4, v35
	v_rcp_f32_e32 v7, v5
	v_div_scale_f32 v9, vcc, v35, v4, v35
	v_fma_f32 v10, -v5, v7, 1.0
	v_fmac_f32_e32 v7, v10, v7
	v_mul_f32_e32 v10, v9, v7
	v_fma_f32 v11, -v5, v10, v9
	v_fmac_f32_e32 v10, v11, v7
	v_fma_f32 v5, -v5, v10, v9
	v_div_fmas_f32 v5, v5, v7, v10
	v_div_fixup_f32 v12, v5, v4, v35
	ds_write_b32 v6, v12 offset:30720
	s_waitcnt vmcnt(1)
	v_mul_f32_e32 v4, 0xbfb8aa3b, v36
	v_rndne_f32_e32 v5, v4
	v_fma_f32 v8, v36, s42, -v4
	v_sub_f32_e32 v4, v4, v5
	v_fmac_f32_e32 v8, 0xb2a5705f, v36
	v_add_f32_e32 v4, v4, v8
	v_exp_f32_e32 v4, v4
	v_cvt_i32_f32_e32 v5, v5
	v_cmp_nlt_f32_e64 s[40:41], s43, v36
	v_ldexp_f32 v4, v4, v5
	s_nop 1
	v_cndmask_b32_e64 v4, 0, v4, s[40:41]
	v_cmp_ngt_f32_e64 s[40:41], s8, v36
	s_nop 1
	v_cndmask_b32_e64 v4, v228, v4, s[40:41]
	v_add_f32_e32 v4, 1.0, v4
	v_div_scale_f32 v5, s[4:5], v4, v4, v36
	v_rcp_f32_e32 v7, v5
	v_div_scale_f32 v9, vcc, v36, v4, v36
	v_fma_f32 v10, -v5, v7, 1.0
	v_fmac_f32_e32 v7, v10, v7
	v_mul_f32_e32 v10, v9, v7
	v_fma_f32 v11, -v5, v10, v9
	v_fmac_f32_e32 v10, v11, v7
	v_fma_f32 v5, -v5, v10, v9
	v_div_fmas_f32 v5, v5, v7, v10
	v_div_fixup_f32 v12, v5, v4, v36
	ds_write_b32 v6, v12 offset:32768
	s_waitcnt vmcnt(0)
	v_mul_f32_e32 v4, 0xbfb8aa3b, v37
	v_rndne_f32_e32 v5, v4
	v_fma_f32 v8, v37, s42, -v4
	v_sub_f32_e32 v4, v4, v5
	v_fmac_f32_e32 v8, 0xb2a5705f, v37
	v_add_f32_e32 v4, v4, v8
	v_exp_f32_e32 v4, v4
	v_cvt_i32_f32_e32 v5, v5
	v_cmp_nlt_f32_e64 s[40:41], s43, v37
	v_ldexp_f32 v4, v4, v5
	s_nop 1
	v_cndmask_b32_e64 v4, 0, v4, s[40:41]
	v_cmp_ngt_f32_e64 s[40:41], s8, v37
	s_nop 1
	v_cndmask_b32_e64 v4, v228, v4, s[40:41]
	v_add_f32_e32 v4, 1.0, v4
	v_div_scale_f32 v5, s[4:5], v4, v4, v37
	v_rcp_f32_e32 v7, v5
	v_div_scale_f32 v9, vcc, v37, v4, v37
	v_fma_f32 v10, -v5, v7, 1.0
	v_fmac_f32_e32 v7, v10, v7
	v_mul_f32_e32 v10, v9, v7
	v_fma_f32 v11, -v5, v10, v9
	v_fmac_f32_e32 v10, v11, v7
	v_fma_f32 v5, -v5, v10, v9
	v_div_fmas_f32 v5, v5, v7, v10
	v_div_fixup_f32 v12, v5, v4, v37
	ds_write_b32 v6, v12 offset:34816

; #define GAS __attribute__((address_space(1)))
; __global__ void __launch_bounds__(512, 2) fwd_mega(Args args) {
;     ...
;                 for (int item = bx; item < DEPTH * 36; item += G) {
;                     const int l = item / 36, n0 = (item % 36) * 256;
;                     f32x4 acc[9];
; #pragma unroll
;                     for (int r = 0; r < 9; ++r) acc[r] = (f32x4){0.f, 0.f, 0.f, 0.f};
;                     const GAS float* w = (const GAS float*)ap->in[4] + (size_t)l * DM * (NMOD * DM) + (size_t)(wave * 128) * (NMOD * DM) + n0 + 4 * lane;
; #pragma unroll 16
;                     for (int kk = 0; kk < 128; ++kk) {
;                         const f32x4 wv = *(const GAS f32x4*)(w + (size_t)kk * (NMOD * DM));
; #pragma unroll
;                         for (int r = 0; r < 9; ++r) acc[r] += wv * S[r * DM + wave * 128 + kk];
.LBB0_1167:
	v_mov_b64_e32 v[2:3], s[0:1]
	flat_load_dwordx2 v[38:39], v[2:3] offset:32
	s_mul_hi_i32 s4, s83, 0x38e38e39
	s_lshr_b32 s5, s4, 31
	s_ashr_i32 s24, s4, 3
	s_add_i32 s24, s24, s5
	s_mul_i32 s4, s24, 36
	s_sub_i32 s4, s83, s4
	s_lshl_b32 s14, s4, 8
	s_ashr_i32 s15, s14, 31
	s_mul_i32 s6, s24, 0x2400000
	s_lshl_b64 s[20:21], s[14:15], 2
	s_mul_hi_i32 s5, s24, 0x2400000
	s_add_u32 s4, s6, s20
	v_mov_b32_e32 v2, 0
	s_addc_u32 s5, s5, s21
	s_mov_b64 s[26:27], 0
	s_mov_b32 s22, s31
	v_mov_b32_e32 v3, v2
	v_mov_b32_e32 v4, v2
	v_mov_b32_e32 v5, v2
	v_mov_b32_e32 v6, v2
	v_mov_b32_e32 v7, v2
	v_mov_b32_e32 v8, v2
	v_mov_b32_e32 v9, v2
	v_mov_b32_e32 v10, v2
	v_mov_b32_e32 v11, v2
	v_mov_b32_e32 v12, v2
	v_mov_b32_e32 v13, v2
	v_mov_b32_e32 v14, v2
	v_mov_b32_e32 v15, v2
	v_mov_b32_e32 v16, v2
	v_mov_b32_e32 v17, v2
	v_mov_b32_e32 v18, v2
	v_mov_b32_e32 v19, v2
	v_mov_b32_e32 v20, v2
	v_mov_b32_e32 v21, v2
	v_mov_b32_e32 v22, v2
	v_mov_b32_e32 v23, v2
	v_mov_b32_e32 v24, v2
	v_mov_b32_e32 v25, v2
	v_mov_b32_e32 v26, v2
	v_mov_b32_e32 v27, v2
	v_mov_b32_e32 v28, v2
	v_mov_b32_e32 v29, v2
	v_mov_b32_e32 v30, v2
	v_mov_b32_e32 v31, v2
	v_mov_b32_e32 v32, v2
	v_mov_b32_e32 v33, v2
	v_mov_b32_e32 v34, v2
	v_mov_b32_e32 v35, v2
	v_mov_b32_e32 v36, v2
	v_mov_b32_e32 v37, v2
	s_waitcnt vmcnt(0) lgkmcnt(0)
	v_lshl_add_u64 v[38:39], v[38:39], 0, s[18:19]
	v_lshl_add_u64 v[38:39], v[38:39], 0, v[50:51]
	v_lshl_add_u64 v[52:53], v[38:39], 0, s[4:5]
	s_mov_b64 s[6:7], 0x9000
.LBB0_1168:
	v_lshl_add_u64 v[54:55], v[52:53], 0, s[26:27]
	global_load_dwordx4 v[100:103], v[54:55], off
	v_lshl_add_u64 v[60:61], v[54:55], 0, s[6:7]
	global_load_dwordx4 v[104:107], v[60:61], off
	v_lshl_add_u64 v[60:61], v[60:61], 0, s[6:7]
	global_load_dwordx4 v[108:111], v[60:61], off
	v_lshl_add_u64 v[60:61], v[60:61], 0, s[6:7]
	global_load_dwordx4 v[112:115], v[60:61], off
	v_lshl_add_u64 v[60:61], v[60:61], 0, s[6:7]
	global_load_dwordx4 v[116:119], v[60:61], off
	v_lshl_add_u64 v[60:61], v[60:61], 0, s[6:7]
	global_load_dwordx4 v[120:123], v[60:61], off
	v_lshl_add_u64 v[60:61], v[60:61], 0, s[6:7]
	global_load_dwordx4 v[124:127], v[60:61], off
	v_lshl_add_u64 v[60:61], v[60:61], 0, s[6:7]
	global_load_dwordx4 v[128:131], v[60:61], off
	v_lshl_add_u64 v[60:61], v[60:61], 0, s[6:7]
	global_load_dwordx4 v[132:135], v[60:61], off
	v_lshl_add_u64 v[60:61], v[60:61], 0, s[6:7]
	global_load_dwordx4 v[136:139], v[60:61], off
	v_lshl_add_u64 v[60:61], v[60:61], 0, s[6:7]
	global_load_dwordx4 v[140:143], v[60:61], off
	v_lshl_add_u64 v[60:61], v[60:61], 0, s[6:7]
	global_load_dwordx4 v[144:147], v[60:61], off
	v_lshl_add_u64 v[60:61], v[60:61], 0, s[6:7]
	global_load_dwordx4 v[148:151], v[60:61], off
	v_lshl_add_u64 v[60:61], v[60:61], 0, s[6:7]
	global_load_dwordx4 v[152:155], v[60:61], off
	v_lshl_add_u64 v[60:61], v[60:61], 0, s[6:7]
	global_load_dwordx4 v[156:159], v[60:61], off
	v_lshl_add_u64 v[60:61], v[60:61], 0, s[6:7]
	global_load_dwordx4 v[160:163], v[60:61], off
	v_mov_b32_e32 v0, s22
	s_add_u32 s26, s26, 0x90000
	s_addc_u32 s27, s27, 0
	s_add_i32 s22, s22, 64
	ds_read_b128 v[64:67], v0
	ds_read_b128 v[68:71], v0 offset:4096
	ds_read_b128 v[72:75], v0 offset:8192
	ds_read_b128 v[76:79], v0 offset:12288
	ds_read_b128 v[80:83], v0 offset:16384
	ds_read_b128 v[84:87], v0 offset:20480
	ds_read_b128 v[88:91], v0 offset:24576
	ds_read_b128 v[92:95], v0 offset:28672
	ds_read_b128 v[96:99], v0 offset:32768
	s_waitcnt lgkmcnt(0)
	s_waitcnt vmcnt(15)
	v_pk_fma_f32 v[2:3], v[100:101], v[64:65], v[2:3] op_sel_hi:[1,0,1]
	v_pk_fma_f32 v[4:5], v[102:103], v[64:65], v[4:5] op_sel_hi:[1,0,1]
	v_pk_fma_f32 v[6:7], v[100:101], v[68:69], v[6:7] op_sel_hi:[1,0,1]
	v_pk_fma_f32 v[8:9], v[102:103], v[68:69], v[8:9] op_sel_hi:[1,0,1]
	v_pk_fma_f32 v[10:11], v[100:101], v[72:73], v[10:11] op_sel_hi:[1,0,1]
	v_pk_fma_f32 v[12:13], v[102:103], v[72:73], v[12:13] op_sel_hi:[1,0,1]
	v_pk_fma_f32 v[14:15], v[100:101], v[76:77], v[14:15] op_sel_hi:[1,0,1]
	v_pk_fma_f32 v[16:17], v[102:103], v[76:77], v[16:17] op_sel_hi:[1,0,1]
	v_pk_fma_f32 v[18:19], v[100:101], v[80:81], v[18:19] op_sel_hi:[1,0,1]
	v_pk_fma_f32 v[20:21], v[102:103], v[80:81], v[20:21] op_sel_hi:[1,0,1]
	v_pk_fma_f32 v[22:23], v[100:101], v[84:85], v[22:23] op_sel_hi:[1,0,1]
	v_pk_fma_f32 v[24:25], v[102:103], v[84:85], v[24:25] op_sel_hi:[1,0,1]
	v_pk_fma_f32 v[26:27], v[100:101], v[88:89], v[26:27] op_sel_hi:[1,0,1]
	v_pk_fma_f32 v[28:29], v[102:103], v[88:89], v[28:29] op_sel_hi:[1,0,1]
	v_pk_fma_f32 v[30:31], v[100:101], v[92:93], v[30:31] op_sel_hi:[1,0,1]
	v_pk_fma_f32 v[32:33], v[102:103], v[92:93], v[32:33] op_sel_hi:[1,0,1]
	v_pk_fma_f32 v[34:35], v[100:101], v[96:97], v[34:35] op_sel_hi:[1,0,1]
	v_pk_fma_f32 v[36:37], v[102:103], v[96:97], v[36:37] op_sel_hi:[1,0,1]
	s_waitcnt vmcnt(14)
	v_pk_fma_f32 v[2:3], v[104:105], v[64:65], v[2:3] op_sel:[0,1,0]
	v_pk_fma_f32 v[4:5], v[106:107], v[64:65], v[4:5] op_sel:[0,1,0]
	v_pk_fma_f32 v[6:7], v[104:105], v[68:69], v[6:7] op_sel:[0,1,0]
	v_pk_fma_f32 v[8:9], v[106:107], v[68:69], v[8:9] op_sel:[0,1,0]
	v_pk_fma_f32 v[10:11], v[104:105], v[72:73], v[10:11] op_sel:[0,1,0]
	v_pk_fma_f32 v[12:13], v[106:107], v[72:73], v[12:13] op_sel:[0,1,0]
	v_pk_fma_f32 v[14:15], v[104:105], v[76:77], v[14:15] op_sel:[0,1,0]
	v_pk_fma_f32 v[16:17], v[106:107], v[76:77], v[16:17] op_sel:[0,1,0]
	v_pk_fma_f32 v[18:19], v[104:105], v[80:81], v[18:19] op_sel:[0,1,0]
	v_pk_fma_f32 v[20:21], v[106:107], v[80:81], v[20:21] op_sel:[0,1,0]
	v_pk_fma_f32 v[22:23], v[104:105], v[84:85], v[22:23] op_sel:[0,1,0]
	v_pk_fma_f32 v[24:25], v[106:107], v[84:85], v[24:25] op_sel:[0,1,0]
	v_pk_fma_f32 v[26:27], v[104:105], v[88:89], v[26:27] op_sel:[0,1,0]
	v_pk_fma_f32 v[28:29], v[106:107], v[88:89], v[28:29] op_sel:[0,1,0]
	v_pk_fma_f32 v[30:31], v[104:105], v[92:93], v[30:31] op_sel:[0,1,0]
	v_pk_fma_f32 v[32:33], v[106:107], v[92:93], v[32:33] op_sel:[0,1,0]
	v_pk_fma_f32 v[34:35], v[104:105], v[96:97], v[34:35] op_sel:[0,1,0]
	v_pk_fma_f32 v[36:37], v[106:107], v[96:97], v[36:37] op_sel:[0,1,0]
	s_waitcnt vmcnt(13)
; #define GAS __attribute__((address_space(1)))
; __global__ void __launch_bounds__(512, 2) fwd_mega(Args args) {
;     ...
;                     for (int kk = 0; kk < 128; ++kk) {
;                         const f32x4 wv = *(const GAS f32x4*)(w + (size_t)kk * (NMOD * DM));
; #pragma unroll
;                         for (int r = 0; r < 9; ++r) acc[r] += wv * S[r * DM + wave * 128 + kk];
	v_pk_fma_f32 v[2:3], v[108:109], v[66:67], v[2:3] op_sel_hi:[1,0,1]
	v_pk_fma_f32 v[4:5], v[110:111], v[66:67], v[4:5] op_sel_hi:[1,0,1]
	v_pk_fma_f32 v[6:7], v[108:109], v[70:71], v[6:7] op_sel_hi:[1,0,1]
	v_pk_fma_f32 v[8:9], v[110:111], v[70:71], v[8:9] op_sel_hi:[1,0,1]
	v_pk_fma_f32 v[10:11], v[108:109], v[74:75], v[10:11] op_sel_hi:[1,0,1]
	v_pk_fma_f32 v[12:13], v[110:111], v[74:75], v[12:13] op_sel_hi:[1,0,1]
	v_pk_fma_f32 v[14:15], v[108:109], v[78:79], v[14:15] op_sel_hi:[1,0,1]
	v_pk_fma_f32 v[16:17], v[110:111], v[78:79], v[16:17] op_sel_hi:[1,0,1]
	v_pk_fma_f32 v[18:19], v[108:109], v[82:83], v[18:19] op_sel_hi:[1,0,1]
	v_pk_fma_f32 v[20:21], v[110:111], v[82:83], v[20:21] op_sel_hi:[1,0,1]
	v_pk_fma_f32 v[22:23], v[108:109], v[86:87], v[22:23] op_sel_hi:[1,0,1]
	v_pk_fma_f32 v[24:25], v[110:111], v[86:87], v[24:25] op_sel_hi:[1,0,1]
	v_pk_fma_f32 v[26:27], v[108:109], v[90:91], v[26:27] op_sel_hi:[1,0,1]
	v_pk_fma_f32 v[28:29], v[110:111], v[90:91], v[28:29] op_sel_hi:[1,0,1]
	v_pk_fma_f32 v[30:31], v[108:109], v[94:95], v[30:31] op_sel_hi:[1,0,1]
	v_pk_fma_f32 v[32:33], v[110:111], v[94:95], v[32:33] op_sel_hi:[1,0,1]
	v_pk_fma_f32 v[34:35], v[108:109], v[98:99], v[34:35] op_sel_hi:[1,0,1]
	v_pk_fma_f32 v[36:37], v[110:111], v[98:99], v[36:37] op_sel_hi:[1,0,1]
	s_waitcnt vmcnt(12)
	v_pk_fma_f32 v[2:3], v[112:113], v[66:67], v[2:3] op_sel:[0,1,0]
	v_pk_fma_f32 v[4:5], v[114:115], v[66:67], v[4:5] op_sel:[0,1,0]
	v_pk_fma_f32 v[6:7], v[112:113], v[70:71], v[6:7] op_sel:[0,1,0]
	v_pk_fma_f32 v[8:9], v[114:115], v[70:71], v[8:9] op_sel:[0,1,0]
	v_pk_fma_f32 v[10:11], v[112:113], v[74:75], v[10:11] op_sel:[0,1,0]
	v_pk_fma_f32 v[12:13], v[114:115], v[74:75], v[12:13] op_sel:[0,1,0]
	v_pk_fma_f32 v[14:15], v[112:113], v[78:79], v[14:15] op_sel:[0,1,0]
	v_pk_fma_f32 v[16:17], v[114:115], v[78:79], v[16:17] op_sel:[0,1,0]
	v_pk_fma_f32 v[18:19], v[112:113], v[82:83], v[18:19] op_sel:[0,1,0]
	v_pk_fma_f32 v[20:21], v[114:115], v[82:83], v[20:21] op_sel:[0,1,0]
	v_pk_fma_f32 v[22:23], v[112:113], v[86:87], v[22:23] op_sel:[0,1,0]
	v_pk_fma_f32 v[24:25], v[114:115], v[86:87], v[24:25] op_sel:[0,1,0]
	v_pk_fma_f32 v[26:27], v[112:113], v[90:91], v[26:27] op_sel:[0,1,0]
	v_pk_fma_f32 v[28:29], v[114:115], v[90:91], v[28:29] op_sel:[0,1,0]
	v_pk_fma_f32 v[30:31], v[112:113], v[94:95], v[30:31] op_sel:[0,1,0]
	v_pk_fma_f32 v[32:33], v[114:115], v[94:95], v[32:33] op_sel:[0,1,0]
	v_pk_fma_f32 v[34:35], v[112:113], v[98:99], v[34:35] op_sel:[0,1,0]
	v_pk_fma_f32 v[36:37], v[114:115], v[98:99], v[36:37] op_sel:[0,1,0]
	ds_read_b128 v[64:67], v0 offset:16
	ds_read_b128 v[68:71], v0 offset:4112
	ds_read_b128 v[72:75], v0 offset:8208
	ds_read_b128 v[76:79], v0 offset:12304
	ds_read_b128 v[80:83], v0 offset:16400
	ds_read_b128 v[84:87], v0 offset:20496
	ds_read_b128 v[88:91], v0 offset:24592
	ds_read_b128 v[92:95], v0 offset:28688
	ds_read_b128 v[96:99], v0 offset:32784
	s_waitcnt lgkmcnt(0)
	s_waitcnt vmcnt(11)
	v_pk_fma_f32 v[2:3], v[116:117], v[64:65], v[2:3] op_sel_hi:[1,0,1]
	v_pk_fma_f32 v[4:5], v[118:119], v[64:65], v[4:5] op_sel_hi:[1,0,1]
	v_pk_fma_f32 v[6:7], v[116:117], v[68:69], v[6:7] op_sel_hi:[1,0,1]
	v_pk_fma_f32 v[8:9], v[118:119], v[68:69], v[8:9] op_sel_hi:[1,0,1]
	v_pk_fma_f32 v[10:11], v[116:117], v[72:73], v[10:11] op_sel_hi:[1,0,1]
	v_pk_fma_f32 v[12:13], v[118:119], v[72:73], v[12:13] op_sel_hi:[1,0,1]
	v_pk_fma_f32 v[14:15], v[116:117], v[76:77], v[14:15] op_sel_hi:[1,0,1]
	v_pk_fma_f32 v[16:17], v[118:119], v[76:77], v[16:17] op_sel_hi:[1,0,1]
	v_pk_fma_f32 v[18:19], v[116:117], v[80:81], v[18:19] op_sel_hi:[1,0,1]
	v_pk_fma_f32 v[20:21], v[118:119], v[80:81], v[20:21] op_sel_hi:[1,0,1]
	v_pk_fma_f32 v[22:23], v[116:117], v[84:85], v[22:23] op_sel_hi:[1,0,1]
	v_pk_fma_f32 v[24:25], v[118:119], v[84:85], v[24:25] op_sel_hi:[1,0,1]
	v_pk_fma_f32 v[26:27], v[116:117], v[88:89], v[26:27] op_sel_hi:[1,0,1]
	v_pk_fma_f32 v[28:29], v[118:119], v[88:89], v[28:29] op_sel_hi:[1,0,1]
	v_pk_fma_f32 v[30:31], v[116:117], v[92:93], v[30:31] op_sel_hi:[1,0,1]
	v_pk_fma_f32 v[32:33], v[118:119], v[92:93], v[32:33] op_sel_hi:[1,0,1]
	v_pk_fma_f32 v[34:35], v[116:117], v[96:97], v[34:35] op_sel_hi:[1,0,1]
	v_pk_fma_f32 v[36:37], v[118:119], v[96:97], v[36:37] op_sel_hi:[1,0,1]
	s_waitcnt vmcnt(10)
	v_pk_fma_f32 v[2:3], v[120:121], v[64:65], v[2:3] op_sel:[0,1,0]
	v_pk_fma_f32 v[4:5], v[122:123], v[64:65], v[4:5] op_sel:[0,1,0]
	v_pk_fma_f32 v[6:7], v[120:121], v[68:69], v[6:7] op_sel:[0,1,0]
	v_pk_fma_f32 v[8:9], v[122:123], v[68:69], v[8:9] op_sel:[0,1,0]
	v_pk_fma_f32 v[10:11], v[120:121], v[72:73], v[10:11] op_sel:[0,1,0]
	v_pk_fma_f32 v[12:13], v[122:123], v[72:73], v[12:13] op_sel:[0,1,0]
	v_pk_fma_f32 v[14:15], v[120:121], v[76:77], v[14:15] op_sel:[0,1,0]
	v_pk_fma_f32 v[16:17], v[122:123], v[76:77], v[16:17] op_sel:[0,1,0]
	v_pk_fma_f32 v[18:19], v[120:121], v[80:81], v[18:19] op_sel:[0,1,0]
	v_pk_fma_f32 v[20:21], v[122:123], v[80:81], v[20:21] op_sel:[0,1,0]
	v_pk_fma_f32 v[22:23], v[120:121], v[84:85], v[22:23] op_sel:[0,1,0]
	v_pk_fma_f32 v[24:25], v[122:123], v[84:85], v[24:25] op_sel:[0,1,0]
	v_pk_fma_f32 v[26:27], v[120:121], v[88:89], v[26:27] op_sel:[0,1,0]
	v_pk_fma_f32 v[28:29], v[122:123], v[88:89], v[28:29] op_sel:[0,1,0]
	v_pk_fma_f32 v[30:31], v[120:121], v[92:93], v[30:31] op_sel:[0,1,0]
	v_pk_fma_f32 v[32:33], v[122:123], v[92:93], v[32:33] op_sel:[0,1,0]
	v_pk_fma_f32 v[34:35], v[120:121], v[96:97], v[34:35] op_sel:[0,1,0]
	v_pk_fma_f32 v[36:37], v[122:123], v[96:97], v[36:37] op_sel:[0,1,0]
	s_waitcnt vmcnt(9)
; #define GAS __attribute__((address_space(1)))
; __global__ void __launch_bounds__(512, 2) fwd_mega(Args args) {
;     ...
;                     for (int kk = 0; kk < 128; ++kk) {
;                         const f32x4 wv = *(const GAS f32x4*)(w + (size_t)kk * (NMOD * DM));
; #pragma unroll
;                         for (int r = 0; r < 9; ++r) acc[r] += wv * S[r * DM + wave * 128 + kk];
	v_pk_fma_f32 v[2:3], v[124:125], v[66:67], v[2:3] op_sel_hi:[1,0,1]
	v_pk_fma_f32 v[4:5], v[126:127], v[66:67], v[4:5] op_sel_hi:[1,0,1]
	v_pk_fma_f32 v[6:7], v[124:125], v[70:71], v[6:7] op_sel_hi:[1,0,1]
	v_pk_fma_f32 v[8:9], v[126:127], v[70:71], v[8:9] op_sel_hi:[1,0,1]
	v_pk_fma_f32 v[10:11], v[124:125], v[74:75], v[10:11] op_sel_hi:[1,0,1]
	v_pk_fma_f32 v[12:13], v[126:127], v[74:75], v[12:13] op_sel_hi:[1,0,1]
	v_pk_fma_f32 v[14:15], v[124:125], v[78:79], v[14:15] op_sel_hi:[1,0,1]
	v_pk_fma_f32 v[16:17], v[126:127], v[78:79], v[16:17] op_sel_hi:[1,0,1]
	v_pk_fma_f32 v[18:19], v[124:125], v[82:83], v[18:19] op_sel_hi:[1,0,1]
	v_pk_fma_f32 v[20:21], v[126:127], v[82:83], v[20:21] op_sel_hi:[1,0,1]
	v_pk_fma_f32 v[22:23], v[124:125], v[86:87], v[22:23] op_sel_hi:[1,0,1]
	v_pk_fma_f32 v[24:25], v[126:127], v[86:87], v[24:25] op_sel_hi:[1,0,1]
	v_pk_fma_f32 v[26:27], v[124:125], v[90:91], v[26:27] op_sel_hi:[1,0,1]
	v_pk_fma_f32 v[28:29], v[126:127], v[90:91], v[28:29] op_sel_hi:[1,0,1]
	v_pk_fma_f32 v[30:31], v[124:125], v[94:95], v[30:31] op_sel_hi:[1,0,1]
	v_pk_fma_f32 v[32:33], v[126:127], v[94:95], v[32:33] op_sel_hi:[1,0,1]
	v_pk_fma_f32 v[34:35], v[124:125], v[98:99], v[34:35] op_sel_hi:[1,0,1]
	v_pk_fma_f32 v[36:37], v[126:127], v[98:99], v[36:37] op_sel_hi:[1,0,1]
	s_waitcnt vmcnt(8)
	v_pk_fma_f32 v[2:3], v[128:129], v[66:67], v[2:3] op_sel:[0,1,0]
	v_pk_fma_f32 v[4:5], v[130:131], v[66:67], v[4:5] op_sel:[0,1,0]
	v_pk_fma_f32 v[6:7], v[128:129], v[70:71], v[6:7] op_sel:[0,1,0]
	v_pk_fma_f32 v[8:9], v[130:131], v[70:71], v[8:9] op_sel:[0,1,0]
	v_pk_fma_f32 v[10:11], v[128:129], v[74:75], v[10:11] op_sel:[0,1,0]
	v_pk_fma_f32 v[12:13], v[130:131], v[74:75], v[12:13] op_sel:[0,1,0]
	v_pk_fma_f32 v[14:15], v[128:129], v[78:79], v[14:15] op_sel:[0,1,0]
	v_pk_fma_f32 v[16:17], v[130:131], v[78:79], v[16:17] op_sel:[0,1,0]
	v_pk_fma_f32 v[18:19], v[128:129], v[82:83], v[18:19] op_sel:[0,1,0]
	v_pk_fma_f32 v[20:21], v[130:131], v[82:83], v[20:21] op_sel:[0,1,0]
	v_pk_fma_f32 v[22:23], v[128:129], v[86:87], v[22:23] op_sel:[0,1,0]
	v_pk_fma_f32 v[24:25], v[130:131], v[86:87], v[24:25] op_sel:[0,1,0]
	v_pk_fma_f32 v[26:27], v[128:129], v[90:91], v[26:27] op_sel:[0,1,0]
	v_pk_fma_f32 v[28:29], v[130:131], v[90:91], v[28:29] op_sel:[0,1,0]
	v_pk_fma_f32 v[30:31], v[128:129], v[94:95], v[30:31] op_sel:[0,1,0]
	v_pk_fma_f32 v[32:33], v[130:131], v[94:95], v[32:33] op_sel:[0,1,0]
	v_pk_fma_f32 v[34:35], v[128:129], v[98:99], v[34:35] op_sel:[0,1,0]
	v_pk_fma_f32 v[36:37], v[130:131], v[98:99], v[36:37] op_sel:[0,1,0]
	ds_read_b128 v[64:67], v0 offset:32
	ds_read_b128 v[68:71], v0 offset:4128
	ds_read_b128 v[72:75], v0 offset:8224
	ds_read_b128 v[76:79], v0 offset:12320
	ds_read_b128 v[80:83], v0 offset:16416
	ds_read_b128 v[84:87], v0 offset:20512
	ds_read_b128 v[88:91], v0 offset:24608
	ds_read_b128 v[92:95], v0 offset:28704
	ds_read_b128 v[96:99], v0 offset:32800
	s_waitcnt lgkmcnt(0)
	s_waitcnt vmcnt(7)
	v_pk_fma_f32 v[2:3], v[132:133], v[64:65], v[2:3] op_sel_hi:[1,0,1]
	v_pk_fma_f32 v[4:5], v[134:135], v[64:65], v[4:5] op_sel_hi:[1,0,1]
	v_pk_fma_f32 v[6:7], v[132:133], v[68:69], v[6:7] op_sel_hi:[1,0,1]
	v_pk_fma_f32 v[8:9], v[134:135], v[68:69], v[8:9] op_sel_hi:[1,0,1]
	v_pk_fma_f32 v[10:11], v[132:133], v[72:73], v[10:11] op_sel_hi:[1,0,1]
	v_pk_fma_f32 v[12:13], v[134:135], v[72:73], v[12:13] op_sel_hi:[1,0,1]
	v_pk_fma_f32 v[14:15], v[132:133], v[76:77], v[14:15] op_sel_hi:[1,0,1]
	v_pk_fma_f32 v[16:17], v[134:135], v[76:77], v[16:17] op_sel_hi:[1,0,1]
	v_pk_fma_f32 v[18:19], v[132:133], v[80:81], v[18:19] op_sel_hi:[1,0,1]
	v_pk_fma_f32 v[20:21], v[134:135], v[80:81], v[20:21] op_sel_hi:[1,0,1]
	v_pk_fma_f32 v[22:23], v[132:133], v[84:85], v[22:23] op_sel_hi:[1,0,1]
	v_pk_fma_f32 v[24:25], v[134:135], v[84:85], v[24:25] op_sel_hi:[1,0,1]
	v_pk_fma_f32 v[26:27], v[132:133], v[88:89], v[26:27] op_sel_hi:[1,0,1]
	v_pk_fma_f32 v[28:29], v[134:135], v[88:89], v[28:29] op_sel_hi:[1,0,1]
	v_pk_fma_f32 v[30:31], v[132:133], v[92:93], v[30:31] op_sel_hi:[1,0,1]
	v_pk_fma_f32 v[32:33], v[134:135], v[92:93], v[32:33] op_sel_hi:[1,0,1]
	v_pk_fma_f32 v[34:35], v[132:133], v[96:97], v[34:35] op_sel_hi:[1,0,1]
	v_pk_fma_f32 v[36:37], v[134:135], v[96:97], v[36:37] op_sel_hi:[1,0,1]
	s_waitcnt vmcnt(6)
	v_pk_fma_f32 v[2:3], v[136:137], v[64:65], v[2:3] op_sel:[0,1,0]
	v_pk_fma_f32 v[4:5], v[138:139], v[64:65], v[4:5] op_sel:[0,1,0]
	v_pk_fma_f32 v[6:7], v[136:137], v[68:69], v[6:7] op_sel:[0,1,0]
	v_pk_fma_f32 v[8:9], v[138:139], v[68:69], v[8:9] op_sel:[0,1,0]
	v_pk_fma_f32 v[10:11], v[136:137], v[72:73], v[10:11] op_sel:[0,1,0]
	v_pk_fma_f32 v[12:13], v[138:139], v[72:73], v[12:13] op_sel:[0,1,0]
	v_pk_fma_f32 v[14:15], v[136:137], v[76:77], v[14:15] op_sel:[0,1,0]
	v_pk_fma_f32 v[16:17], v[138:139], v[76:77], v[16:17] op_sel:[0,1,0]
	v_pk_fma_f32 v[18:19], v[136:137], v[80:81], v[18:19] op_sel:[0,1,0]
	v_pk_fma_f32 v[20:21], v[138:139], v[80:81], v[20:21] op_sel:[0,1,0]
	v_pk_fma_f32 v[22:23], v[136:137], v[84:85], v[22:23] op_sel:[0,1,0]
	v_pk_fma_f32 v[24:25], v[138:139], v[84:85], v[24:25] op_sel:[0,1,0]
	v_pk_fma_f32 v[26:27], v[136:137], v[88:89], v[26:27] op_sel:[0,1,0]
	v_pk_fma_f32 v[28:29], v[138:139], v[88:89], v[28:29] op_sel:[0,1,0]
	v_pk_fma_f32 v[30:31], v[136:137], v[92:93], v[30:31] op_sel:[0,1,0]
	v_pk_fma_f32 v[32:33], v[138:139], v[92:93], v[32:33] op_sel:[0,1,0]
	v_pk_fma_f32 v[34:35], v[136:137], v[96:97], v[34:35] op_sel:[0,1,0]
	v_pk_fma_f32 v[36:37], v[138:139], v[96:97], v[36:37] op_sel:[0,1,0]
	s_waitcnt vmcnt(5)
; #define GAS __attribute__((address_space(1)))
; __global__ void __launch_bounds__(512, 2) fwd_mega(Args args) {
;     ...
;                     for (int kk = 0; kk < 128; ++kk) {
;                         const f32x4 wv = *(const GAS f32x4*)(w + (size_t)kk * (NMOD * DM));
; #pragma unroll
;                         for (int r = 0; r < 9; ++r) acc[r] += wv * S[r * DM + wave * 128 + kk];
	v_pk_fma_f32 v[2:3], v[140:141], v[66:67], v[2:3] op_sel_hi:[1,0,1]
	v_pk_fma_f32 v[4:5], v[142:143], v[66:67], v[4:5] op_sel_hi:[1,0,1]
	v_pk_fma_f32 v[6:7], v[140:141], v[70:71], v[6:7] op_sel_hi:[1,0,1]
	v_pk_fma_f32 v[8:9], v[142:143], v[70:71], v[8:9] op_sel_hi:[1,0,1]
	v_pk_fma_f32 v[10:11], v[140:141], v[74:75], v[10:11] op_sel_hi:[1,0,1]
	v_pk_fma_f32 v[12:13], v[142:143], v[74:75], v[12:13] op_sel_hi:[1,0,1]
	v_pk_fma_f32 v[14:15], v[140:141], v[78:79], v[14:15] op_sel_hi:[1,0,1]
	v_pk_fma_f32 v[16:17], v[142:143], v[78:79], v[16:17] op_sel_hi:[1,0,1]
	v_pk_fma_f32 v[18:19], v[140:141], v[82:83], v[18:19] op_sel_hi:[1,0,1]
	v_pk_fma_f32 v[20:21], v[142:143], v[82:83], v[20:21] op_sel_hi:[1,0,1]
	v_pk_fma_f32 v[22:23], v[140:141], v[86:87], v[22:23] op_sel_hi:[1,0,1]
	v_pk_fma_f32 v[24:25], v[142:143], v[86:87], v[24:25] op_sel_hi:[1,0,1]
	v_pk_fma_f32 v[26:27], v[140:141], v[90:91], v[26:27] op_sel_hi:[1,0,1]
	v_pk_fma_f32 v[28:29], v[142:143], v[90:91], v[28:29] op_sel_hi:[1,0,1]
	v_pk_fma_f32 v[30:31], v[140:141], v[94:95], v[30:31] op_sel_hi:[1,0,1]
	v_pk_fma_f32 v[32:33], v[142:143], v[94:95], v[32:33] op_sel_hi:[1,0,1]
	v_pk_fma_f32 v[34:35], v[140:141], v[98:99], v[34:35] op_sel_hi:[1,0,1]
	v_pk_fma_f32 v[36:37], v[142:143], v[98:99], v[36:37] op_sel_hi:[1,0,1]
	s_waitcnt vmcnt(4)
	v_pk_fma_f32 v[2:3], v[144:145], v[66:67], v[2:3] op_sel:[0,1,0]
	v_pk_fma_f32 v[4:5], v[146:147], v[66:67], v[4:5] op_sel:[0,1,0]
	v_pk_fma_f32 v[6:7], v[144:145], v[70:71], v[6:7] op_sel:[0,1,0]
	v_pk_fma_f32 v[8:9], v[146:147], v[70:71], v[8:9] op_sel:[0,1,0]
	v_pk_fma_f32 v[10:11], v[144:145], v[74:75], v[10:11] op_sel:[0,1,0]
	v_pk_fma_f32 v[12:13], v[146:147], v[74:75], v[12:13] op_sel:[0,1,0]
	v_pk_fma_f32 v[14:15], v[144:145], v[78:79], v[14:15] op_sel:[0,1,0]
	v_pk_fma_f32 v[16:17], v[146:147], v[78:79], v[16:17] op_sel:[0,1,0]
	v_pk_fma_f32 v[18:19], v[144:145], v[82:83], v[18:19] op_sel:[0,1,0]
	v_pk_fma_f32 v[20:21], v[146:147], v[82:83], v[20:21] op_sel:[0,1,0]
	v_pk_fma_f32 v[22:23], v[144:145], v[86:87], v[22:23] op_sel:[0,1,0]
	v_pk_fma_f32 v[24:25], v[146:147], v[86:87], v[24:25] op_sel:[0,1,0]
	v_pk_fma_f32 v[26:27], v[144:145], v[90:91], v[26:27] op_sel:[0,1,0]
	v_pk_fma_f32 v[28:29], v[146:147], v[90:91], v[28:29] op_sel:[0,1,0]
	v_pk_fma_f32 v[30:31], v[144:145], v[94:95], v[30:31] op_sel:[0,1,0]
	v_pk_fma_f32 v[32:33], v[146:147], v[94:95], v[32:33] op_sel:[0,1,0]
	v_pk_fma_f32 v[34:35], v[144:145], v[98:99], v[34:35] op_sel:[0,1,0]
	v_pk_fma_f32 v[36:37], v[146:147], v[98:99], v[36:37] op_sel:[0,1,0]
	ds_read_b128 v[64:67], v0 offset:48
	ds_read_b128 v[68:71], v0 offset:4144
	ds_read_b128 v[72:75], v0 offset:8240
	ds_read_b128 v[76:79], v0 offset:12336
	ds_read_b128 v[80:83], v0 offset:16432
	ds_read_b128 v[84:87], v0 offset:20528
	ds_read_b128 v[88:91], v0 offset:24624
	ds_read_b128 v[92:95], v0 offset:28720
	ds_read_b128 v[96:99], v0 offset:32816
	s_waitcnt lgkmcnt(0)
	s_waitcnt vmcnt(3)
	v_pk_fma_f32 v[2:3], v[148:149], v[64:65], v[2:3] op_sel_hi:[1,0,1]
	v_pk_fma_f32 v[4:5], v[150:151], v[64:65], v[4:5] op_sel_hi:[1,0,1]
	v_pk_fma_f32 v[6:7], v[148:149], v[68:69], v[6:7] op_sel_hi:[1,0,1]
	v_pk_fma_f32 v[8:9], v[150:151], v[68:69], v[8:9] op_sel_hi:[1,0,1]
	v_pk_fma_f32 v[10:11], v[148:149], v[72:73], v[10:11] op_sel_hi:[1,0,1]
	v_pk_fma_f32 v[12:13], v[150:151], v[72:73], v[12:13] op_sel_hi:[1,0,1]
	v_pk_fma_f32 v[14:15], v[148:149], v[76:77], v[14:15] op_sel_hi:[1,0,1]
	v_pk_fma_f32 v[16:17], v[150:151], v[76:77], v[16:17] op_sel_hi:[1,0,1]
	v_pk_fma_f32 v[18:19], v[148:149], v[80:81], v[18:19] op_sel_hi:[1,0,1]
	v_pk_fma_f32 v[20:21], v[150:151], v[80:81], v[20:21] op_sel_hi:[1,0,1]
	v_pk_fma_f32 v[22:23], v[148:149], v[84:85], v[22:23] op_sel_hi:[1,0,1]
	v_pk_fma_f32 v[24:25], v[150:151], v[84:85], v[24:25] op_sel_hi:[1,0,1]
	v_pk_fma_f32 v[26:27], v[148:149], v[88:89], v[26:27] op_sel_hi:[1,0,1]
	v_pk_fma_f32 v[28:29], v[150:151], v[88:89], v[28:29] op_sel_hi:[1,0,1]
	v_pk_fma_f32 v[30:31], v[148:149], v[92:93], v[30:31] op_sel_hi:[1,0,1]
	v_pk_fma_f32 v[32:33], v[150:151], v[92:93], v[32:33] op_sel_hi:[1,0,1]
	v_pk_fma_f32 v[34:35], v[148:149], v[96:97], v[34:35] op_sel_hi:[1,0,1]
	v_pk_fma_f32 v[36:37], v[150:151], v[96:97], v[36:37] op_sel_hi:[1,0,1]
	s_waitcnt vmcnt(2)
; #define LAS __attribute__((address_space(3)))
; #define GAS __attribute__((address_space(1)))
; __global__ void __launch_bounds__(512, 2) fwd_mega(Args args) {
;     ...
;                     for (int kk = 0; kk < 128; ++kk) {
;                         const f32x4 wv = *(const GAS f32x4*)(w + (size_t)kk * (NMOD * DM));
; #pragma unroll
;                         for (int r = 0; r < 9; ++r) acc[r] += wv * S[r * DM + wave * 128 + kk];
;                     }
; #pragma unroll
;                     for (int r = 0; r < 9; ++r) *(LAS f32x4*)(red + (wave * 9 + r) * 256 + 4 * lane) = acc[r];
;                     __syncthreads();
;                     for (int o = tid; o < 9 * 256; o += 512) {
;                         const int r = o >> 8, cc = o & 255; float sm = ap->in[5][l * (NMOD * DM) + n0 + cc];
	v_pk_fma_f32 v[2:3], v[152:153], v[64:65], v[2:3] op_sel:[0,1,0]
	v_pk_fma_f32 v[4:5], v[154:155], v[64:65], v[4:5] op_sel:[0,1,0]
	v_pk_fma_f32 v[6:7], v[152:153], v[68:69], v[6:7] op_sel:[0,1,0]
	v_pk_fma_f32 v[8:9], v[154:155], v[68:69], v[8:9] op_sel:[0,1,0]
	v_pk_fma_f32 v[10:11], v[152:153], v[72:73], v[10:11] op_sel:[0,1,0]
	v_pk_fma_f32 v[12:13], v[154:155], v[72:73], v[12:13] op_sel:[0,1,0]
	v_pk_fma_f32 v[14:15], v[152:153], v[76:77], v[14:15] op_sel:[0,1,0]
	v_pk_fma_f32 v[16:17], v[154:155], v[76:77], v[16:17] op_sel:[0,1,0]
	v_pk_fma_f32 v[18:19], v[152:153], v[80:81], v[18:19] op_sel:[0,1,0]
	v_pk_fma_f32 v[20:21], v[154:155], v[80:81], v[20:21] op_sel:[0,1,0]
	v_pk_fma_f32 v[22:23], v[152:153], v[84:85], v[22:23] op_sel:[0,1,0]
	v_pk_fma_f32 v[24:25], v[154:155], v[84:85], v[24:25] op_sel:[0,1,0]
	v_pk_fma_f32 v[26:27], v[152:153], v[88:89], v[26:27] op_sel:[0,1,0]
	v_pk_fma_f32 v[28:29], v[154:155], v[88:89], v[28:29] op_sel:[0,1,0]
	v_pk_fma_f32 v[30:31], v[152:153], v[92:93], v[30:31] op_sel:[0,1,0]
	v_pk_fma_f32 v[32:33], v[154:155], v[92:93], v[32:33] op_sel:[0,1,0]
	v_pk_fma_f32 v[34:35], v[152:153], v[96:97], v[34:35] op_sel:[0,1,0]
	v_pk_fma_f32 v[36:37], v[154:155], v[96:97], v[36:37] op_sel:[0,1,0]
	s_waitcnt vmcnt(1)
	v_pk_fma_f32 v[2:3], v[156:157], v[66:67], v[2:3] op_sel_hi:[1,0,1]
	v_pk_fma_f32 v[4:5], v[158:159], v[66:67], v[4:5] op_sel_hi:[1,0,1]
	v_pk_fma_f32 v[6:7], v[156:157], v[70:71], v[6:7] op_sel_hi:[1,0,1]
	v_pk_fma_f32 v[8:9], v[158:159], v[70:71], v[8:9] op_sel_hi:[1,0,1]
	v_pk_fma_f32 v[10:11], v[156:157], v[74:75], v[10:11] op_sel_hi:[1,0,1]
	v_pk_fma_f32 v[12:13], v[158:159], v[74:75], v[12:13] op_sel_hi:[1,0,1]
	v_pk_fma_f32 v[14:15], v[156:157], v[78:79], v[14:15] op_sel_hi:[1,0,1]
	v_pk_fma_f32 v[16:17], v[158:159], v[78:79], v[16:17] op_sel_hi:[1,0,1]
	v_pk_fma_f32 v[18:19], v[156:157], v[82:83], v[18:19] op_sel_hi:[1,0,1]
	v_pk_fma_f32 v[20:21], v[158:159], v[82:83], v[20:21] op_sel_hi:[1,0,1]
	v_pk_fma_f32 v[22:23], v[156:157], v[86:87], v[22:23] op_sel_hi:[1,0,1]
	v_pk_fma_f32 v[24:25], v[158:159], v[86:87], v[24:25] op_sel_hi:[1,0,1]
	v_pk_fma_f32 v[26:27], v[156:157], v[90:91], v[26:27] op_sel_hi:[1,0,1]
	v_pk_fma_f32 v[28:29], v[158:159], v[90:91], v[28:29] op_sel_hi:[1,0,1]
	v_pk_fma_f32 v[30:31], v[156:157], v[94:95], v[30:31] op_sel_hi:[1,0,1]
	v_pk_fma_f32 v[32:33], v[158:159], v[94:95], v[32:33] op_sel_hi:[1,0,1]
	v_pk_fma_f32 v[34:35], v[156:157], v[98:99], v[34:35] op_sel_hi:[1,0,1]
	v_pk_fma_f32 v[36:37], v[158:159], v[98:99], v[36:37] op_sel_hi:[1,0,1]
	s_waitcnt vmcnt(0)
	v_pk_fma_f32 v[2:3], v[160:161], v[66:67], v[2:3] op_sel:[0,1,0]
	v_pk_fma_f32 v[4:5], v[162:163], v[66:67], v[4:5] op_sel:[0,1,0]
	v_pk_fma_f32 v[6:7], v[160:161], v[70:71], v[6:7] op_sel:[0,1,0]
	v_pk_fma_f32 v[8:9], v[162:163], v[70:71], v[8:9] op_sel:[0,1,0]
	v_pk_fma_f32 v[10:11], v[160:161], v[74:75], v[10:11] op_sel:[0,1,0]
	v_pk_fma_f32 v[12:13], v[162:163], v[74:75], v[12:13] op_sel:[0,1,0]
	v_pk_fma_f32 v[14:15], v[160:161], v[78:79], v[14:15] op_sel:[0,1,0]
	v_pk_fma_f32 v[16:17], v[162:163], v[78:79], v[16:17] op_sel:[0,1,0]
	v_pk_fma_f32 v[18:19], v[160:161], v[82:83], v[18:19] op_sel:[0,1,0]
	v_pk_fma_f32 v[20:21], v[162:163], v[82:83], v[20:21] op_sel:[0,1,0]
	v_pk_fma_f32 v[22:23], v[160:161], v[86:87], v[22:23] op_sel:[0,1,0]
	v_pk_fma_f32 v[24:25], v[162:163], v[86:87], v[24:25] op_sel:[0,1,0]
	v_pk_fma_f32 v[26:27], v[160:161], v[90:91], v[26:27] op_sel:[0,1,0]
	v_pk_fma_f32 v[28:29], v[162:163], v[90:91], v[28:29] op_sel:[0,1,0]
	v_pk_fma_f32 v[30:31], v[160:161], v[94:95], v[30:31] op_sel:[0,1,0]
	v_pk_fma_f32 v[32:33], v[162:163], v[94:95], v[32:33] op_sel:[0,1,0]
	v_pk_fma_f32 v[34:35], v[160:161], v[98:99], v[34:35] op_sel:[0,1,0]
	v_pk_fma_f32 v[36:37], v[162:163], v[98:99], v[36:37] op_sel:[0,1,0]
	s_cmp_lg_u32 s26, 0x480000
	s_cbranch_scc1 .LBB0_1168
	ds_write_b128 v56, v[2:5] offset:36864
	ds_write_b128 v56, v[6:9] offset:37888
	ds_write_b128 v56, v[10:13] offset:38912
	ds_write_b128 v56, v[14:17] offset:39936
	ds_write_b128 v56, v[18:21] offset:40960
	ds_write_b128 v56, v[22:25] offset:41984
	ds_write_b128 v56, v[26:29] offset:43008
	ds_write_b128 v56, v[30:33] offset:44032
	ds_write_b128 v56, v[34:37] offset:45056
	s_waitcnt lgkmcnt(0)
	s_barrier
	s_and_saveexec_b64 s[22:23], vcc
	s_cbranch_execz .LBB0_1166
	v_mov_b64_e32 v[2:3], s[0:1]
	flat_load_dwordx2 v[2:3], v[2:3] offset:40
	s_add_u32 s20, s34, s20
	s_mul_i32 s4, s24, 0x2400
	s_addc_u32 s21, s35, s21
	s_add_i32 s4, s4, s14
	s_mul_i32 s24, s24, 9
	s_mov_b64 s[14:15], 0
	v_mov_b32_e32 v4, v196
